# scan: output-wave read ring + in-place state (no copy block); prep: deferred bf16 shift of prefetched gate rows
# speedup vs baseline: 1.0010x; 1.0010x over previous
.LBB0_649:
	s_or_b64 exec, exec, s[0:1]
	s_lshl_b32 s92, s94, 4
	s_ashr_i32 s93, s92, 31
	s_or_b64 s[0:1], s[48:49], s[54:55]
	v_mov_b32_e32 v17, 0
	v_mov_b32_e32 v148, 0
	s_and_saveexec_b64 s[84:85], s[0:1]
	s_cbranch_execz .LBB0_651
	v_add_u32_e32 v2, s33, v87
	v_mov_b64_e32 v[0:1], s[86:87]
	v_mad_i64_i32 v[0:1], s[0:1], v2, s81, v[0:1]
	v_lshl_add_u64 v[0:1], s[92:93], 1, v[0:1]
	v_lshlrev_b32_e32 v2, 1, v90
	v_mov_b32_e32 v3, v16
	v_lshl_add_u64 v[0:1], v[0:1], 0, v[2:3]
	v_add_co_u32_e32 v0, vcc, 0x3000, v0
	s_nop 1
	v_addc_co_u32_e32 v1, vcc, 0, v1, vcc
	global_load_ushort v0, v[0:1], off
	s_waitcnt vmcnt(0)
	v_mov_b32_e32 v148, v0
.LBB0_651:
	s_or_b64 exec, exec, s[84:85]
	s_or_b64 s[0:1], s[54:55], s[50:51]
	s_and_saveexec_b64 s[54:55], s[0:1]
	s_cbranch_execz .LBB0_653
	v_add_u32_e32 v2, s33, v131
	v_mov_b64_e32 v[0:1], s[86:87]
	v_mad_i64_i32 v[0:1], s[0:1], v2, s81, v[0:1]
	v_lshl_add_u64 v[0:1], s[92:93], 1, v[0:1]
	v_lshlrev_b32_e32 v2, 1, v90
	v_mov_b32_e32 v3, v16
	v_lshl_add_u64 v[0:1], v[0:1], 0, v[2:3]
	v_add_co_u32_e32 v0, vcc, 0x3000, v0
	s_nop 1
	v_addc_co_u32_e32 v1, vcc, 0, v1, vcc
	global_load_ushort v0, v[0:1], off
	s_waitcnt vmcnt(0)
	v_mov_b32_e32 v17, v0

; #define LAS __attribute__((address_space(3)))
; __device__ __forceinline__ void gla_prep_phase(const Ctx& c, int j, LAS unsigned char* lds) {
;     ...
;         for (int jj = 0; jj < 4; ++jj) { const int idx = c.tid + 512 * jj, i = idx >> 5, c16 = idx & 31;
;             *(LAS u32x4*)(QL + i * 528 + c16 * 16) = pq[jj]; *(LAS u32x4*)(KL + i * 528 + c16 * 16) = pk[jj]; }
; #pragma unroll
;         for (int q_ = 0; q_ < 2; ++q_) LR[c.tid + 512 * q_] = plr[q_];
;         float up[16];
; #pragma unroll
;         for (int r = 0; r < 16; ++r) up[r] = pup[r];
;         const float bias = pbias;
;         { const int un = u + c.G; have = un < 2 * 16 * NCH; if (have) PREP_FETCH(un); }
.LBB0_655:
	v_add_u32_e32 v149, v121, v86
	v_readlane_b32 s0, v254, 29
	s_barrier
	ds_write_b128 v149, v[24:27] offset:6144
	ds_write_b128 v149, v[20:23] offset:39936
	v_add_u32_e32 v149, v123, v86
	s_add_i32 s10, s11, s0
	ds_write_b128 v149, v[32:35] offset:6144
	ds_write_b128 v149, v[28:31] offset:39936
	v_add_u32_e32 v149, v125, v86
	s_cmpk_gt_i32 s10, 0x81f
	ds_write_b128 v149, v[40:43] offset:6144
	ds_write_b128 v149, v[36:39] offset:39936
	v_add_u32_e32 v149, v127, v86
	s_cselect_b64 s[92:93], -1, 0
	s_waitcnt vmcnt(2)
	v_mov_b64_e32 v[12:13], v[114:115]
	s_waitcnt vmcnt(0)
	v_mov_b64_e32 v[14:15], v[118:119]
	ds_write_b128 v149, v[48:51] offset:6144
	ds_write_b128 v149, v[44:47] offset:39936
	v_lshlrev_b32_e32 v148, 16, v148
	v_lshlrev_b32_e32 v17, 16, v17
	ds_write2st64_b32 v91, v148, v17 offset1:8
	s_and_b64 vcc, exec, s[92:93]
	v_mov_b32_e32 v149, v105
	s_cbranch_vccnz .LBB0_672
	s_mul_hi_i32 s0, s10, 0x7e07e07f
	s_lshr_b32 s1, s0, 31
	s_ashr_i32 s0, s0, 9
	s_add_i32 s54, s0, s1
	s_mul_i32 s0, s54, 0x410
	s_sub_i32 s0, s10, s0
	s_mul_i32 s1, s0, 0xfc1
	s_lshr_b32 s33, s1, 31
	s_ashr_i32 s1, s1, 18
	s_add_i32 s33, s1, s33
	s_mul_i32 s1, s33, 0x41
	s_sub_i32 s0, s0, s1
	s_ashr_i32 s57, s33, 2
	s_and_b32 s1, s0, 0xffff
	s_cmp_lg_u32 s1, 0
	s_sext_i32_i16 s56, s0
	s_cbranch_scc0 .LBB0_683
	s_lshl_b32 s0, s57, 12
	s_lshl_b32 s1, s56, 6
	s_add_i32 s1, s1, s0
	s_sub_i32 s55, s1, 64
	s_cbranch_execnz .LBB0_659

; __device__ __forceinline__ void gla_prep_phase(const Ctx& c, int j, LAS unsigned char* lds) {
;     ...
;         { const int un = u + c.G; have = un < 2 * 16 * NCH; if (have) PREP_FETCH(un); }
.LBB0_667:
	s_or_b64 exec, exec, s[0:1]
	s_lshl_b32 s84, s54, 4
	s_ashr_i32 s85, s84, 31
	s_or_b64 s[56:57], s[48:49], s[96:97]
	v_mov_b32_e32 v17, 0
	v_lshlrev_b32_e32 v18, 1, v90
	v_mov_b32_e32 v148, 0
	s_and_saveexec_b64 s[0:1], s[56:57]
	s_cbranch_execz .LBB0_669
	v_add_u32_e32 v19, s55, v87
	v_mov_b64_e32 v[106:107], s[86:87]
	v_mad_i64_i32 v[106:107], s[56:57], v19, s81, v[106:107]
	v_lshl_add_u64 v[106:107], s[84:85], 1, v[106:107]
	v_mov_b32_e32 v19, v16
	v_lshl_add_u64 v[106:107], v[106:107], 0, v[18:19]
	v_add_co_u32_e32 v106, vcc, 0x3000, v106
	s_nop 1
	v_addc_co_u32_e32 v107, vcc, 0, v107, vcc
	global_load_ushort v148, v[106:107], off
.LBB0_669:
	s_or_b64 exec, exec, s[0:1]
	s_or_b64 s[56:57], s[50:51], s[96:97]
	s_and_saveexec_b64 s[0:1], s[56:57]
	s_cbranch_execz .LBB0_671
	v_add_u32_e32 v17, s55, v131
	v_mov_b64_e32 v[106:107], s[86:87]
	v_mad_i64_i32 v[106:107], s[56:57], v17, s81, v[106:107]
	v_lshl_add_u64 v[106:107], s[84:85], 1, v[106:107]
	v_mov_b32_e32 v19, v16
	v_lshl_add_u64 v[18:19], v[106:107], 0, v[18:19]
	v_add_co_u32_e32 v18, vcc, 0x3000, v18
	s_nop 1
	v_addc_co_u32_e32 v19, vcc, 0, v19, vcc
	global_load_ushort v17, v[18:19], off
.LBB0_671:
	s_or_b64 exec, exec, s[0:1]
	s_ashr_i32 s55, s54, 31
	v_readlane_b32 s56, v254, 0
	s_lshl_b64 s[0:1], s[54:55], 16
	v_readlane_b32 s58, v254, 2
	v_readlane_b32 s59, v254, 3
	s_add_u32 s0, s58, s0
	s_addc_u32 s1, s59, s1
	s_lshl_b32 s33, s33, 2
	s_add_u32 s0, s0, s33
	s_addc_u32 s1, s1, 0
	v_lshlrev_b32_e32 v150, 2, v52
	v_mov_b32_e32 v151, v16
	v_lshl_add_u64 v[152:153], s[0:1], 0, v[150:151]
	v_add_co_u32_e32 v106, vcc, s82, v152
	global_load_dword v18, v150, s[0:1]
	s_nop 0
	v_addc_co_u32_e32 v107, vcc, 0, v153, vcc
	v_add_co_u32_e32 v112, vcc, s83, v152
	global_load_dword v108, v[106:107], off offset:-4096
	s_nop 0
	global_load_dword v106, v[106:107], off
	v_addc_co_u32_e32 v113, vcc, 0, v153, vcc
	global_load_dword v110, v[112:113], off offset:-4096
	global_load_dword v19, v[112:113], off
	v_add_co_u32_e32 v112, vcc, s79, v152
	v_readlane_b32 s60, v254, 4
	s_nop 0
	v_addc_co_u32_e32 v113, vcc, 0, v153, vcc
	global_load_dword v109, v[112:113], off offset:-4096
	global_load_dword v107, v[112:113], off
	v_add_co_u32_e32 v112, vcc, s80, v152
	s_lshl_b64 s[0:1], s[54:55], 12
	s_nop 0
	v_addc_co_u32_e32 v113, vcc, 0, v153, vcc
	v_add_co_u32_e32 v114, vcc, s2, v152
	v_readlane_b32 s61, v254, 5
	s_nop 0
	v_addc_co_u32_e32 v115, vcc, 0, v153, vcc
	v_add_co_u32_e32 v154, vcc, s3, v152
	global_load_dword v111, v[112:113], off offset:-4096
	s_nop 0
	global_load_dword v112, v[112:113], off
	v_addc_co_u32_e32 v155, vcc, 0, v153, vcc
	global_load_dword v116, v[114:115], off offset:-4096
	s_nop 0
	global_load_dword v114, v[114:115], off
	s_nop 0
	global_load_dword v118, v[154:155], off offset:-4096
	global_load_dword v113, v[154:155], off
	v_add_co_u32_e32 v154, vcc, s4, v152
	s_add_u32 s0, s60, s0
	s_nop 0
	v_addc_co_u32_e32 v155, vcc, 0, v153, vcc
	s_addc_u32 s1, s61, s1
	v_add_co_u32_e32 v152, vcc, s5, v152
	s_add_u32 s0, s0, s33
	s_nop 0
	v_addc_co_u32_e32 v153, vcc, 0, v153, vcc
	s_addc_u32 s1, s1, 0
	global_load_dword v117, v[154:155], off offset:-4096
	global_load_dword v115, v[154:155], off
	global_load_dword v119, v[152:153], off
	global_load_dword v149, v150, s[0:1]
	v_readlane_b32 s57, v254, 1
	v_readlane_b32 s62, v254, 6
	v_readlane_b32 s63, v254, 7

; #define LAS __attribute__((address_space(3)))
; __device__ __forceinline__ void gla_scan_phase(const Ctx& c, LAS unsigned char* lds) {
;     ...
;                 __builtin_amdgcn_s_setprio(2);
; #pragma unroll
;                 for (int t = 0; t < 4; ++t) { const int db = 2 * jj + (t >> 1);
; #pragma unroll
;                     for (int g4 = 0; g4 < 4; ++g4) { const f32x4 dv = *(const LAS f32x4*)(lds + SC_DEC + (32 * db + 8 * g4 + 4 * hi) * 4);
;                         sacc[t][4 * g4 + 0] *= dv.x; sacc[t][4 * g4 + 1] *= dv.y; sacc[t][4 * g4 + 2] *= dv.z; sacc[t][4 * g4 + 3] *= dv.w; } }
; #pragma unroll
;                 for (int ks = 0; ks < 4; ++ks) {
;                     const bf16x8 a0 = *(const LAS bf16x8*)(lds + SC_KT + (64 * jj + r32) * 144 + (ks * 16 + hi * 8) * 2);
;                     const bf16x8 a1 = *(const LAS bf16x8*)(lds + SC_KT + (64 * jj + 32 + r32) * 144 + (ks * 16 + hi * 8) * 2);
;                     const bf16x8 b0 = *(const LAS bf16x8*)(lds + SC_VT + r32 * 144 + (ks * 16 + hi * 8) * 2);
;                     const bf16x8 b1 = *(const LAS bf16x8*)(lds + SC_VT + (32 + r32) * 144 + (ks * 16 + hi * 8) * 2);
;                     sacc[0] = __builtin_amdgcn_mfma_f32_32x32x16_bf16(a0, b0, sacc[0], 0, 0, 0);
;                     sacc[1] = __builtin_amdgcn_mfma_f32_32x32x16_bf16(a0, b1, sacc[1], 0, 0, 0);
;                     sacc[2] = __builtin_amdgcn_mfma_f32_32x32x16_bf16(a1, b0, sacc[2], 0, 0, 0);
;                     sacc[3] = __builtin_amdgcn_mfma_f32_32x32x16_bf16(a1, b1, sacc[3], 0, 0, 0); }
.LBB0_758:
	s_mov_b64 s[84:85], -1
	s_and_b64 vcc, exec, s[20:21]
	s_cbranch_vccz .LBB0_760
	s_setprio 2
	ds_read_b128 v[2:5], v205
	ds_read_b128 v[6:9], v205 offset:32
	ds_read_b128 v[10:13], v205 offset:64
	ds_read_b128 v[96:99], v205 offset:96
	s_mov_b64 s[84:85], 0
	s_waitcnt lgkmcnt(3)
	v_pk_mul_f32 v[66:67], v[66:67], v[4:5]
	s_waitcnt lgkmcnt(2)
	v_pk_mul_f32 v[68:69], v[68:69], v[6:7]
	s_waitcnt lgkmcnt(1)
	v_pk_mul_f32 v[72:73], v[72:73], v[10:11]
	s_waitcnt lgkmcnt(0)
	v_pk_mul_f32 v[76:77], v[76:77], v[96:97]
	v_pk_mul_f32 v[78:79], v[78:79], v[98:99]
	v_pk_mul_f32 v[74:75], v[74:75], v[12:13]
	v_pk_mul_f32 v[70:71], v[70:71], v[8:9]
	v_pk_mul_f32 v[64:65], v[64:65], v[2:3]
	v_pk_mul_f32 v[60:61], v[60:61], v[96:97]
	v_pk_mul_f32 v[56:57], v[56:57], v[10:11]
	v_pk_mul_f32 v[52:53], v[52:53], v[6:7]
	v_pk_mul_f32 v[62:63], v[62:63], v[98:99]
	v_pk_mul_f32 v[58:59], v[58:59], v[12:13]
	v_pk_mul_f32 v[54:55], v[54:55], v[8:9]
	v_pk_mul_f32 v[50:51], v[50:51], v[4:5]
	v_pk_mul_f32 v[48:49], v[48:49], v[2:3]
	ds_read_b128 v[2:5], v205 offset:128
	ds_read_b128 v[6:9], v205 offset:160
	ds_read_b128 v[10:13], v205 offset:192
	ds_read_b128 v[128:131], v205 offset:224
	s_waitcnt lgkmcnt(3)
	v_pk_mul_f32 v[34:35], v[34:35], v[4:5]
	s_waitcnt lgkmcnt(2)
	v_pk_mul_f32 v[36:37], v[36:37], v[6:7]
	s_waitcnt lgkmcnt(1)
	v_pk_mul_f32 v[40:41], v[40:41], v[10:11]
	s_waitcnt lgkmcnt(0)
	v_pk_mul_f32 v[44:45], v[44:45], v[128:129]
	v_pk_mul_f32 v[46:47], v[46:47], v[130:131]
	v_pk_mul_f32 v[42:43], v[42:43], v[12:13]
	v_pk_mul_f32 v[38:39], v[38:39], v[8:9]
	v_pk_mul_f32 v[32:33], v[32:33], v[2:3]
	v_pk_mul_f32 v[28:29], v[28:29], v[128:129]
	v_pk_mul_f32 v[24:25], v[24:25], v[10:11]
	v_pk_mul_f32 v[20:21], v[20:21], v[6:7]
	v_pk_mul_f32 v[30:31], v[30:31], v[130:131]
	v_pk_mul_f32 v[26:27], v[26:27], v[12:13]
	v_pk_mul_f32 v[22:23], v[22:23], v[8:9]
	v_pk_mul_f32 v[18:19], v[18:19], v[4:5]
	v_pk_mul_f32 v[16:17], v[16:17], v[2:3]
	ds_read_b128 v[2:5], v206 offset:38400
	ds_read_b128 v[6:9], v207 offset:4608
	ds_read_b128 v[10:13], v206 offset:33792
	ds_read_b128 v[210:213], v206 offset:33824
	ds_read_b128 v[214:217], v207
	ds_read_b128 v[218:221], v207 offset:32
	s_waitcnt lgkmcnt(1)
	v_mfma_f32_32x32x16_bf16 v[64:79], v[10:13], v[214:217], v[64:79]
	v_mfma_f32_32x32x16_bf16 v[48:63], v[10:13], v[6:9], v[48:63]
	v_mfma_f32_32x32x16_bf16 v[32:47], v[2:5], v[214:217], v[32:47]
	v_mfma_f32_32x32x16_bf16 v[16:31], v[2:5], v[6:9], v[16:31]
	ds_read_b128 v[2:5], v206 offset:38432
	ds_read_b128 v[6:9], v207 offset:4640
	s_waitcnt lgkmcnt(2)
	v_mfma_f32_32x32x16_bf16 v[64:79], v[210:213], v[218:221], v[64:79]
	s_waitcnt lgkmcnt(0)
	v_mfma_f32_32x32x16_bf16 v[48:63], v[210:213], v[6:9], v[48:63]
	v_mfma_f32_32x32x16_bf16 v[32:47], v[2:5], v[218:221], v[32:47]
	v_mfma_f32_32x32x16_bf16 v[16:31], v[2:5], v[6:9], v[16:31]
	ds_read_b128 v[2:5], v206 offset:33856
	ds_read_b128 v[6:9], v206 offset:38464
	ds_read_b128 v[10:13], v207 offset:64
	ds_read_b128 v[210:213], v207 offset:4672
	s_waitcnt lgkmcnt(1)
	v_mfma_f32_32x32x16_bf16 v[64:79], v[2:5], v[10:13], v[64:79]
	s_waitcnt lgkmcnt(0)
	v_mfma_f32_32x32x16_bf16 v[48:63], v[2:5], v[210:213], v[48:63]
	v_mfma_f32_32x32x16_bf16 v[32:47], v[6:9], v[10:13], v[32:47]
	v_mfma_f32_32x32x16_bf16 v[16:31], v[6:9], v[210:213], v[16:31]
	ds_read_b128 v[2:5], v206 offset:33888
	ds_read_b128 v[6:9], v206 offset:38496
	ds_read_b128 v[10:13], v207 offset:96
	ds_read_b128 v[210:213], v207 offset:4704
	s_waitcnt lgkmcnt(1)
	v_mfma_f32_32x32x16_bf16 v[64:79], v[2:5], v[10:13], v[64:79]
	s_waitcnt lgkmcnt(0)
	v_mfma_f32_32x32x16_bf16 v[48:63], v[2:5], v[210:213], v[48:63]
	v_mfma_f32_32x32x16_bf16 v[32:47], v[6:9], v[10:13], v[32:47]
	v_mfma_f32_32x32x16_bf16 v[16:31], v[6:9], v[210:213], v[16:31]
; __device__ __forceinline__ void gla_scan_phase(const Ctx& c, LAS unsigned char* lds) {
;     ...
;             if (wid < 4) {
;                 const int ib = wid & 1, eb = wid >> 1; f32x16 acc2 = {};
; #pragma unroll 4
;                 for (int ks = 0; ks < 16; ks += 2) {
;                     const bf16x8 a = *(const LAS bf16x8*)(lds + SC_QD + (32 * ib + r32) * 528 + (ks * 16 + hi * 8) * 2);
;                     const bf16x8 bb = *(const LAS bf16x8*)(lds + SC_ST + (32 * eb + r32) * 528 + (ks * 16 + hi * 8) * 2);
;                     const bf16x8 a2 = *(const LAS bf16x8*)(lds + SC_QD + (32 * ib + r32) * 528 + ((ks + 1) * 16 + hi * 8) * 2);
;                     const bf16x8 bb2 = *(const LAS bf16x8*)(lds + SC_ST + (32 * eb + r32) * 528 + ((ks + 1) * 16 + hi * 8) * 2);
;                     acc = __builtin_amdgcn_mfma_f32_32x32x16_bf16(a, bb, acc, 0, 0, 0);
;                     acc2 = __builtin_amdgcn_mfma_f32_32x32x16_bf16(a2, bb2, acc2, 0, 0, 0); }
; #pragma unroll
;                 for (int ks = 0; ks < 4; ks += 2) {
;                     const bf16x8 a = *(const LAS bf16x8*)(lds + SC_PM + (32 * ib + r32) * 144 + (ks * 16 + hi * 8) * 2);
;                     const bf16x8 bb = *(const LAS bf16x8*)(lds + SC_VT + (32 * eb + r32) * 144 + (ks * 16 + hi * 8) * 2);
;                     const bf16x8 a2 = *(const LAS bf16x8*)(lds + SC_PM + (32 * ib + r32) * 144 + ((ks + 1) * 16 + hi * 8) * 2);
;                     const bf16x8 bb2 = *(const LAS bf16x8*)(lds + SC_VT + (32 * eb + r32) * 144 + ((ks + 1) * 16 + hi * 8) * 2);
;                     acc = __builtin_amdgcn_mfma_f32_32x32x16_bf16(a, bb, acc, 0, 0, 0);
;                     acc2 = __builtin_amdgcn_mfma_f32_32x32x16_bf16(a2, bb2, acc2, 0, 0, 0); }
; #pragma unroll
;                 for (int r = 0; r < 16; ++r) acc[r] += acc2[r];
;     ...
;             __builtin_amdgcn_s_setprio(0);
;             __syncthreads();
;             if (wid >= 4) { const int jj = wid - 4;
; #pragma unroll
;                 for (int t = 0; t < 4; ++t) { const int db = 2 * jj + (t >> 1), eb = t & 1;
; #pragma unroll
;                     for (int g4 = 0; g4 < 4; ++g4) { u32x2 w; w.x = pk2(sacc[t][4 * g4], sacc[t][4 * g4 + 1]); w.y = pk2(sacc[t][4 * g4 + 2], sacc[t][4 * g4 + 3]);
;                         *(LAS u32x2*)(lds + SC_ST + (32 * eb + r32) * 528 + (32 * db + 8 * g4 + 4 * hi) * 2) = w; } } }
.LBB0_760:
	v_mov_b32_e32 v3, 0
	s_andn2_b64 vcc, exec, s[84:85]
	v_mov_b32_e32 v2, 0
	v_mov_b32_e32 v5, 0
	v_mov_b32_e32 v4, 0
	v_mov_b32_e32 v7, 0
	v_mov_b32_e32 v6, 0
	v_mov_b32_e32 v9, 0
	v_mov_b32_e32 v8, 0
	v_mov_b32_e32 v11, 0
	v_mov_b32_e32 v10, 0
	v_mov_b32_e32 v13, 0
	v_mov_b32_e32 v12, 0
	v_mov_b32_e32 v15, 0
	v_mov_b32_e32 v14, 0
	v_mov_b32_e32 v195, 0
	v_mov_b32_e32 v194, 0
	s_cbranch_vccnz .Lscan_join_a
	v_add_u32_e32 v72, v197, v196
	v_add_u32_e32 v73, v204, v196
	v_add_u32_e32 v73, 0x15c00, v73
	ds_read_b128 v[16:19], v72
	ds_read_b128 v[20:23], v73
	ds_read_b128 v[24:27], v72 offset:32
	ds_read_b128 v[28:31], v73 offset:32
	ds_read_b128 v[32:35], v72 offset:64
	ds_read_b128 v[36:39], v73 offset:64
	ds_read_b128 v[40:43], v72 offset:96
	ds_read_b128 v[44:47], v73 offset:96
	ds_read_b128 v[48:51], v72 offset:128
	ds_read_b128 v[52:55], v73 offset:128
	ds_read_b128 v[56:59], v72 offset:160
	ds_read_b128 v[60:63], v73 offset:160
	ds_read_b128 v[64:67], v72 offset:192
	ds_read_b128 v[68:71], v73 offset:192
	s_waitcnt lgkmcnt(12)
	v_mfma_f32_32x32x16_bf16 v[80:95], v[16:19], v[20:23], 0
	ds_read_b128 v[16:19], v72 offset:224
	ds_read_b128 v[20:23], v73 offset:224
	s_waitcnt lgkmcnt(12)
	v_mfma_f32_32x32x16_bf16 v[96:111], v[24:27], v[28:31], 0
	ds_read_b128 v[24:27], v72 offset:256
	ds_read_b128 v[28:31], v73 offset:256
	s_waitcnt lgkmcnt(12)
	v_mfma_f32_32x32x16_bf16 v[80:95], v[32:35], v[36:39], v[80:95]
	ds_read_b128 v[32:35], v72 offset:288
	ds_read_b128 v[36:39], v73 offset:288
	s_waitcnt lgkmcnt(12)
	v_mfma_f32_32x32x16_bf16 v[96:111], v[40:43], v[44:47], v[96:111]
	ds_read_b128 v[40:43], v72 offset:320
	ds_read_b128 v[44:47], v73 offset:320
	s_waitcnt lgkmcnt(12)
	v_mfma_f32_32x32x16_bf16 v[80:95], v[48:51], v[52:55], v[80:95]
	ds_read_b128 v[48:51], v72 offset:352
	ds_read_b128 v[52:55], v73 offset:352
	s_waitcnt lgkmcnt(12)
	v_mfma_f32_32x32x16_bf16 v[96:111], v[56:59], v[60:63], v[96:111]
	ds_read_b128 v[56:59], v72 offset:384
	ds_read_b128 v[60:63], v73 offset:384
	s_waitcnt lgkmcnt(12)
	v_mfma_f32_32x32x16_bf16 v[80:95], v[64:67], v[68:71], v[80:95]
	ds_read_b128 v[64:67], v72 offset:416
	ds_read_b128 v[68:71], v73 offset:416
	s_waitcnt lgkmcnt(12)
	v_mfma_f32_32x32x16_bf16 v[96:111], v[16:19], v[20:23], v[96:111]
	ds_read_b128 v[16:19], v72 offset:448
	ds_read_b128 v[20:23], v73 offset:448
	s_waitcnt lgkmcnt(12)
	v_mfma_f32_32x32x16_bf16 v[80:95], v[24:27], v[28:31], v[80:95]
	ds_read_b128 v[24:27], v72 offset:480
	ds_read_b128 v[28:31], v73 offset:480
	s_waitcnt lgkmcnt(12)
	v_mfma_f32_32x32x16_bf16 v[96:111], v[32:35], v[36:39], v[96:111]
	ds_read_b128 v[32:35], v208
	ds_read_b128 v[36:39], v209
	s_waitcnt lgkmcnt(12)
	v_mfma_f32_32x32x16_bf16 v[80:95], v[40:43], v[44:47], v[80:95]
	ds_read_b128 v[40:43], v208 offset:32
	ds_read_b128 v[44:47], v209 offset:32
	s_waitcnt lgkmcnt(12)
	v_mfma_f32_32x32x16_bf16 v[96:111], v[48:51], v[52:55], v[96:111]
	ds_read_b128 v[48:51], v208 offset:64
	ds_read_b128 v[52:55], v209 offset:64
	s_waitcnt lgkmcnt(12)
	v_mfma_f32_32x32x16_bf16 v[80:95], v[56:59], v[60:63], v[80:95]
	ds_read_b128 v[56:59], v208 offset:96
	ds_read_b128 v[60:63], v209 offset:96
	s_waitcnt lgkmcnt(12)
	v_mfma_f32_32x32x16_bf16 v[96:111], v[64:67], v[68:71], v[96:111]
	s_waitcnt lgkmcnt(10)
	v_mfma_f32_32x32x16_bf16 v[80:95], v[16:19], v[20:23], v[80:95]
	s_waitcnt lgkmcnt(8)
	v_mfma_f32_32x32x16_bf16 v[96:111], v[24:27], v[28:31], v[96:111]
	s_waitcnt lgkmcnt(6)
	v_mfma_f32_32x32x16_bf16 v[80:95], v[32:35], v[36:39], v[80:95]
	s_waitcnt lgkmcnt(4)
	v_mfma_f32_32x32x16_bf16 v[96:111], v[40:43], v[44:47], v[96:111]
	s_waitcnt lgkmcnt(2)
	v_mfma_f32_32x32x16_bf16 v[80:95], v[48:51], v[52:55], v[80:95]
	s_waitcnt lgkmcnt(0)
	v_mfma_f32_32x32x16_bf16 v[96:111], v[56:59], v[60:63], v[96:111]
	s_nop 11
	v_pk_add_f32 v[2:3], v[94:95], v[110:111]
	v_pk_add_f32 v[4:5], v[92:93], v[108:109]
	v_pk_add_f32 v[6:7], v[90:91], v[106:107]
	v_pk_add_f32 v[8:9], v[88:89], v[104:105]
	v_pk_add_f32 v[10:11], v[86:87], v[102:103]
	v_pk_add_f32 v[12:13], v[84:85], v[100:101]
	v_pk_add_f32 v[14:15], v[82:83], v[98:99]
	v_pk_add_f32 v[194:195], v[80:81], v[96:97]
	s_branch .Lscan_join_a
.Lscan_join_a:
	s_setprio 0
	s_andn2_b64 vcc, exec, s[20:21]
	s_barrier
	s_cbranch_vccnz .LBB0_766
	v_cvt_pk_bf16_f32 v80, v64, v65
	v_cvt_pk_bf16_f32 v81, v66, v67
	v_add_u32_e32 v1, s33, v201
	v_cvt_pk_bf16_f32 v82, v68, v69
	v_cvt_pk_bf16_f32 v83, v70, v71
	ds_write2_b64 v1, v[80:81], v[82:83] offset1:2
	v_cvt_pk_bf16_f32 v80, v72, v73
	v_cvt_pk_bf16_f32 v81, v74, v75
	v_cvt_pk_bf16_f32 v82, v76, v77
	v_cvt_pk_bf16_f32 v83, v78, v79
	ds_write2_b64 v1, v[80:81], v[82:83] offset0:4 offset1:6
	v_add_u32_e32 v1, s97, v201
	v_cvt_pk_bf16_f32 v80, v48, v49
	v_cvt_pk_bf16_f32 v81, v50, v51
	v_cvt_pk_bf16_f32 v82, v52, v53
	v_cvt_pk_bf16_f32 v83, v54, v55
	v_add_u32_e32 v1, 0x4000, v1
	ds_write2_b64 v1, v[80:81], v[82:83] offset1:2
	v_cvt_pk_bf16_f32 v80, v56, v57
	v_cvt_pk_bf16_f32 v81, v58, v59
	v_cvt_pk_bf16_f32 v82, v60, v61
	v_cvt_pk_bf16_f32 v83, v62, v63
	ds_write2_b64 v1, v[80:81], v[82:83] offset0:4 offset1:6
	v_cvt_pk_bf16_f32 v80, v32, v33
	v_cvt_pk_bf16_f32 v81, v34, v35
	v_add_u32_e32 v84, s76, v201
	v_cvt_pk_bf16_f32 v82, v36, v37
	v_cvt_pk_bf16_f32 v83, v38, v39
	ds_write2_b64 v84, v[80:81], v[82:83] offset1:2
	v_cvt_pk_bf16_f32 v80, v40, v41
	v_cvt_pk_bf16_f32 v81, v42, v43
	v_cvt_pk_bf16_f32 v82, v44, v45
	v_cvt_pk_bf16_f32 v83, v46, v47
	ds_write2_b64 v84, v[80:81], v[82:83] offset0:4 offset1:6
	v_cvt_pk_bf16_f32 v80, v16, v17
	v_cvt_pk_bf16_f32 v81, v18, v19
	v_cvt_pk_bf16_f32 v82, v20, v21
	v_cvt_pk_bf16_f32 v83, v22, v23
	ds_write2_b64 v1, v[80:81], v[82:83] offset0:8 offset1:10
	v_cvt_pk_bf16_f32 v80, v24, v25
	v_cvt_pk_bf16_f32 v81, v26, v27
	v_cvt_pk_bf16_f32 v82, v28, v29
	v_cvt_pk_bf16_f32 v83, v30, v31
	ds_write2_b64 v1, v[80:81], v[82:83] offset0:12 offset1:14

.LBB0_1605:
	s_or_b64 exec, exec, s[0:1]
	s_lshl_b32 s64, s94, 4
	s_ashr_i32 s65, s64, 31
	s_or_b64 s[0:1], s[48:49], s[54:55]
	v_mov_b32_e32 v17, 0
	v_mov_b32_e32 v148, 0
	s_and_saveexec_b64 s[66:67], s[0:1]
	s_cbranch_execz .LBB0_1607
	v_add_u32_e32 v2, s58, v87
	v_mov_b64_e32 v[0:1], s[56:57]
	v_mad_i64_i32 v[0:1], s[0:1], v2, s79, v[0:1]
	v_lshl_add_u64 v[0:1], s[64:65], 1, v[0:1]
	v_lshlrev_b32_e32 v2, 1, v90
	v_mov_b32_e32 v3, v16
	v_lshl_add_u64 v[0:1], v[0:1], 0, v[2:3]
	v_add_co_u32_e32 v0, vcc, 0x3000, v0
	s_nop 1
	v_addc_co_u32_e32 v1, vcc, 0, v1, vcc
	global_load_ushort v0, v[0:1], off
	s_waitcnt vmcnt(0)
	v_mov_b32_e32 v148, v0
.LBB0_1607:
	s_or_b64 exec, exec, s[66:67]
	s_or_b64 s[0:1], s[54:55], s[50:51]
	s_and_saveexec_b64 s[54:55], s[0:1]
	s_cbranch_execz .LBB0_1609
	v_add_u32_e32 v2, s58, v131
	v_mov_b64_e32 v[0:1], s[56:57]
	v_mad_i64_i32 v[0:1], s[0:1], v2, s79, v[0:1]
	v_lshl_add_u64 v[0:1], s[64:65], 1, v[0:1]
	v_lshlrev_b32_e32 v2, 1, v90
	v_mov_b32_e32 v3, v16
	v_lshl_add_u64 v[0:1], v[0:1], 0, v[2:3]
	v_add_co_u32_e32 v0, vcc, 0x3000, v0
	s_nop 1
	v_addc_co_u32_e32 v1, vcc, 0, v1, vcc
	global_load_ushort v0, v[0:1], off
	s_waitcnt vmcnt(0)
	v_mov_b32_e32 v17, v0

; #define LAS __attribute__((address_space(3)))
; __device__ __forceinline__ void gla_prep_phase(const Ctx& c, int j, LAS unsigned char* lds) {
;     ...
;         for (int jj = 0; jj < 4; ++jj) { const int idx = c.tid + 512 * jj, i = idx >> 5, c16 = idx & 31;
;             *(LAS u32x4*)(QL + i * 528 + c16 * 16) = pq[jj]; *(LAS u32x4*)(KL + i * 528 + c16 * 16) = pk[jj]; }
; #pragma unroll
;         for (int q_ = 0; q_ < 2; ++q_) LR[c.tid + 512 * q_] = plr[q_];
;         float up[16];
; #pragma unroll
;         for (int r = 0; r < 16; ++r) up[r] = pup[r];
;         const float bias = pbias;
;         { const int un = u + c.G; have = un < 2 * 16 * NCH; if (have) PREP_FETCH(un); }
.LBB0_1611:
	v_add_u32_e32 v149, v121, v86
	v_readlane_b32 s0, v254, 29
	s_barrier
	ds_write_b128 v149, v[24:27] offset:6144
	ds_write_b128 v149, v[20:23] offset:39936
	v_add_u32_e32 v149, v123, v86
	s_add_i32 s92, s93, s0
	ds_write_b128 v149, v[32:35] offset:6144
	ds_write_b128 v149, v[28:31] offset:39936
	v_add_u32_e32 v149, v125, v86
	s_cmpk_gt_i32 s92, 0x81f
	ds_write_b128 v149, v[40:43] offset:6144
	ds_write_b128 v149, v[36:39] offset:39936
	v_add_u32_e32 v149, v127, v86
	s_cselect_b64 s[64:65], -1, 0
	s_waitcnt vmcnt(2)
	v_mov_b64_e32 v[12:13], v[114:115]
	s_waitcnt vmcnt(0)
	v_mov_b64_e32 v[14:15], v[118:119]
	ds_write_b128 v149, v[48:51] offset:6144
	ds_write_b128 v149, v[44:47] offset:39936
	v_lshlrev_b32_e32 v148, 16, v148
	v_lshlrev_b32_e32 v17, 16, v17
	ds_write2st64_b32 v91, v148, v17 offset1:8
	s_and_b64 vcc, exec, s[64:65]
	v_mov_b32_e32 v149, v105
	s_cbranch_vccnz .LBB0_1628
	s_mul_hi_i32 s0, s92, 0x7e07e07f
	s_lshr_b32 s1, s0, 31
	s_ashr_i32 s33, s0, 9
	s_add_i32 s33, s33, s1
	s_mul_i32 s0, s33, 0x410
	s_sub_i32 s0, s92, s0
	s_mul_i32 s1, s0, 0xfc1
	s_lshr_b32 s54, s1, 31
	s_ashr_i32 s58, s1, 18
	s_add_i32 s58, s58, s54
	s_mul_i32 s1, s58, 0x41
	s_sub_i32 s0, s0, s1
	s_ashr_i32 s55, s58, 2
	s_and_b32 s1, s0, 0xffff
	s_cmp_lg_u32 s1, 0
	s_sext_i32_i16 s54, s0
	s_cbranch_scc0 .LBB0_1639
	s_lshl_b32 s0, s55, 12
	s_lshl_b32 s1, s54, 6
	s_add_i32 s1, s1, s0
	s_sub_i32 s59, s1, 64
	s_cbranch_execnz .LBB0_1615

; __device__ __forceinline__ void gla_prep_phase(const Ctx& c, int j, LAS unsigned char* lds) {
;     ...
;         { const int un = u + c.G; have = un < 2 * 16 * NCH; if (have) PREP_FETCH(un); }
.LBB0_1623:
	s_or_b64 exec, exec, s[0:1]
	s_lshl_b32 s66, s33, 4
	s_ashr_i32 s67, s66, 31
	s_or_b64 vcc, s[48:49], s[54:55]
	v_mov_b32_e32 v17, 0
	v_lshlrev_b32_e32 v18, 1, v90
	v_mov_b32_e32 v148, 0
	s_and_saveexec_b64 s[0:1], vcc
	s_cbranch_execz .LBB0_1625
	v_add_u32_e32 v19, s59, v87
	v_mov_b64_e32 v[106:107], s[56:57]
	v_mad_i64_i32 v[106:107], vcc, v19, s79, v[106:107]
	v_lshl_add_u64 v[106:107], s[66:67], 1, v[106:107]
	v_mov_b32_e32 v19, v16
	v_lshl_add_u64 v[106:107], v[106:107], 0, v[18:19]
	v_add_co_u32_e32 v106, vcc, 0x3000, v106
	s_nop 1
	v_addc_co_u32_e32 v107, vcc, 0, v107, vcc
	global_load_ushort v148, v[106:107], off
.LBB0_1625:
	s_or_b64 exec, exec, s[0:1]
	s_or_b64 s[54:55], s[50:51], s[54:55]
	s_and_saveexec_b64 s[0:1], s[54:55]
	s_cbranch_execz .LBB0_1627
	v_add_u32_e32 v17, s59, v131
	v_mov_b64_e32 v[106:107], s[56:57]
	v_mad_i64_i32 v[106:107], s[54:55], v17, s79, v[106:107]
	v_lshl_add_u64 v[106:107], s[66:67], 1, v[106:107]
	v_mov_b32_e32 v19, v16
	v_lshl_add_u64 v[18:19], v[106:107], 0, v[18:19]
	v_add_co_u32_e32 v18, vcc, 0x3000, v18
	s_nop 1
	v_addc_co_u32_e32 v19, vcc, 0, v19, vcc
	global_load_ushort v17, v[18:19], off
.LBB0_1627:
	s_or_b64 exec, exec, s[0:1]
	s_add_i32 s54, s33, 2
	s_ashr_i32 s55, s54, 31
	v_readlane_b32 s68, v254, 0
	s_lshl_b64 s[0:1], s[54:55], 16
	v_readlane_b32 s70, v254, 2
	v_readlane_b32 s71, v254, 3
	s_add_u32 s0, s70, s0
	s_addc_u32 s1, s71, s1
	s_lshl_b32 s33, s58, 2
	s_add_u32 s0, s0, s33
	s_addc_u32 s1, s1, 0
	v_lshlrev_b32_e32 v150, 2, v52
	v_mov_b32_e32 v151, v16
	v_lshl_add_u64 v[152:153], s[0:1], 0, v[150:151]
	v_add_co_u32_e32 v106, vcc, s80, v152
	global_load_dword v18, v150, s[0:1]
	s_nop 0
	v_addc_co_u32_e32 v107, vcc, 0, v153, vcc
	v_add_co_u32_e32 v112, vcc, s81, v152
	global_load_dword v108, v[106:107], off offset:-4096
	s_nop 0
	global_load_dword v106, v[106:107], off
	v_addc_co_u32_e32 v113, vcc, 0, v153, vcc
	global_load_dword v110, v[112:113], off offset:-4096
	global_load_dword v19, v[112:113], off
	v_add_co_u32_e32 v112, vcc, s82, v152
	v_readlane_b32 s72, v254, 4
	s_nop 0
	v_addc_co_u32_e32 v113, vcc, 0, v153, vcc
	global_load_dword v109, v[112:113], off offset:-4096
	global_load_dword v107, v[112:113], off
	v_add_co_u32_e32 v112, vcc, s83, v152
	s_lshl_b64 s[0:1], s[54:55], 12
	s_nop 0
	v_addc_co_u32_e32 v113, vcc, 0, v153, vcc
	v_add_co_u32_e32 v114, vcc, s84, v152
	v_readlane_b32 s73, v254, 5
	s_nop 0
	v_addc_co_u32_e32 v115, vcc, 0, v153, vcc
	v_add_co_u32_e32 v154, vcc, s85, v152
	global_load_dword v111, v[112:113], off offset:-4096
	s_nop 0
	global_load_dword v112, v[112:113], off
	v_addc_co_u32_e32 v155, vcc, 0, v153, vcc
	global_load_dword v116, v[114:115], off offset:-4096
	s_nop 0
	global_load_dword v114, v[114:115], off
	s_nop 0
	global_load_dword v118, v[154:155], off offset:-4096
	global_load_dword v113, v[154:155], off
	v_add_co_u32_e32 v154, vcc, s86, v152
	s_add_u32 s0, s72, s0
	s_nop 0
	v_addc_co_u32_e32 v155, vcc, 0, v153, vcc
	s_addc_u32 s1, s73, s1
	v_add_co_u32_e32 v152, vcc, s87, v152
	s_add_u32 s0, s0, s33
	s_nop 0
	v_addc_co_u32_e32 v153, vcc, 0, v153, vcc
	s_addc_u32 s1, s1, 0
	global_load_dword v117, v[154:155], off offset:-4096
	global_load_dword v115, v[154:155], off
	global_load_dword v119, v[152:153], off
	global_load_dword v149, v150, s[0:1]
	v_readlane_b32 s69, v254, 1
	v_readlane_b32 s74, v254, 6
	v_readlane_b32 s75, v254, 7

; #define LAS __attribute__((address_space(3)))
; __device__ __forceinline__ void gla_scan_phase(const Ctx& c, LAS unsigned char* lds) {
;     ...
;                 __builtin_amdgcn_s_setprio(2);
; #pragma unroll
;                 for (int t = 0; t < 4; ++t) { const int db = 2 * jj + (t >> 1);
; #pragma unroll
;                     for (int g4 = 0; g4 < 4; ++g4) { const f32x4 dv = *(const LAS f32x4*)(lds + SC_DEC + (32 * db + 8 * g4 + 4 * hi) * 4);
;                         sacc[t][4 * g4 + 0] *= dv.x; sacc[t][4 * g4 + 1] *= dv.y; sacc[t][4 * g4 + 2] *= dv.z; sacc[t][4 * g4 + 3] *= dv.w; } }
; #pragma unroll
;                 for (int ks = 0; ks < 4; ++ks) {
;                     const bf16x8 a0 = *(const LAS bf16x8*)(lds + SC_KT + (64 * jj + r32) * 144 + (ks * 16 + hi * 8) * 2);
;                     const bf16x8 a1 = *(const LAS bf16x8*)(lds + SC_KT + (64 * jj + 32 + r32) * 144 + (ks * 16 + hi * 8) * 2);
;                     const bf16x8 b0 = *(const LAS bf16x8*)(lds + SC_VT + r32 * 144 + (ks * 16 + hi * 8) * 2);
;                     const bf16x8 b1 = *(const LAS bf16x8*)(lds + SC_VT + (32 + r32) * 144 + (ks * 16 + hi * 8) * 2);
;                     sacc[0] = __builtin_amdgcn_mfma_f32_32x32x16_bf16(a0, b0, sacc[0], 0, 0, 0);
;                     sacc[1] = __builtin_amdgcn_mfma_f32_32x32x16_bf16(a0, b1, sacc[1], 0, 0, 0);
;                     sacc[2] = __builtin_amdgcn_mfma_f32_32x32x16_bf16(a1, b0, sacc[2], 0, 0, 0);
;                     sacc[3] = __builtin_amdgcn_mfma_f32_32x32x16_bf16(a1, b1, sacc[3], 0, 0, 0); }
.LBB0_1714:
	s_mov_b64 s[60:61], -1
	s_and_b64 vcc, exec, s[20:21]
	s_cbranch_vccz .LBB0_1716
	s_setprio 2
	ds_read_b128 v[2:5], v205 offset:96
	ds_read_b128 v[6:9], v205 offset:64
	ds_read_b128 v[10:13], v205 offset:32
	ds_read_b128 v[96:99], v205
	s_mov_b64 s[60:61], 0
	s_waitcnt lgkmcnt(3)
	v_pk_mul_f32 v[76:77], v[76:77], v[2:3]
	v_pk_mul_f32 v[78:79], v[78:79], v[4:5]
	v_pk_mul_f32 v[60:61], v[60:61], v[2:3]
	v_pk_mul_f32 v[62:63], v[62:63], v[4:5]
	ds_read_b128 v[2:5], v206 offset:33792
	s_waitcnt lgkmcnt(3)
	v_pk_mul_f32 v[72:73], v[72:73], v[6:7]
	s_waitcnt lgkmcnt(2)
	v_pk_mul_f32 v[68:69], v[68:69], v[10:11]
	v_pk_mul_f32 v[74:75], v[74:75], v[8:9]
	v_pk_mul_f32 v[70:71], v[70:71], v[12:13]
	v_pk_mul_f32 v[56:57], v[56:57], v[6:7]
	v_pk_mul_f32 v[52:53], v[52:53], v[10:11]
	v_pk_mul_f32 v[58:59], v[58:59], v[8:9]
	v_pk_mul_f32 v[54:55], v[54:55], v[12:13]
	ds_read_b128 v[6:9], v205 offset:128
	ds_read_b128 v[10:13], v205 offset:160
	ds_read_b128 v[128:131], v207
	ds_read_b128 v[132:135], v205 offset:192
	ds_read_b128 v[136:139], v205 offset:224
	ds_read_b128 v[210:213], v206 offset:33824
	ds_read_b128 v[214:217], v207 offset:32
	ds_read_b128 v[218:221], v207 offset:4608
	s_waitcnt lgkmcnt(9)
	v_pk_mul_f32 v[66:67], v[66:67], v[98:99]
	v_pk_mul_f32 v[64:65], v[64:65], v[96:97]
	v_pk_mul_f32 v[50:51], v[50:51], v[98:99]
	v_pk_mul_f32 v[48:49], v[48:49], v[96:97]
	ds_read_b128 v[222:225], v206 offset:38400
	ds_read_b128 v[226:229], v207 offset:4640
	s_waitcnt lgkmcnt(7)
	v_mfma_f32_32x32x16_bf16 v[64:79], v[2:5], v[128:131], v[64:79]
	s_waitcnt lgkmcnt(5)
	v_mul_f32_e64 v44, v44, v136
	v_mul_f32_e64 v45, v45, v137
	v_mul_f32_e64 v40, v40, v132
	v_mul_f32_e64 v41, v41, v133
	v_pk_mul_f32 v[36:37], v[36:37], v[10:11]
	v_pk_mul_f32 v[46:47], v[46:47], v[138:139]
	v_pk_mul_f32 v[42:43], v[42:43], v[134:135]
	v_pk_mul_f32 v[38:39], v[38:39], v[12:13]
	v_pk_mul_f32 v[34:35], v[34:35], v[8:9]
	s_waitcnt lgkmcnt(2)
	v_mfma_f32_32x32x16_bf16 v[48:63], v[2:5], v[218:221], v[48:63]
	v_mul_f32_e64 v32, v32, v6
	v_mul_f32_e64 v33, v33, v7
	v_mul_f32_e64 v28, v28, v136
	v_mul_f32_e64 v29, v29, v137
	ds_read_b128 v[2:5], v206 offset:38432
	v_pk_mul_f32 v[24:25], v[24:25], v[132:133]
	v_pk_mul_f32 v[20:21], v[20:21], v[10:11]
	v_pk_mul_f32 v[30:31], v[30:31], v[138:139]
	v_pk_mul_f32 v[26:27], v[26:27], v[134:135]
	s_waitcnt lgkmcnt(2)
	v_mfma_f32_32x32x16_bf16 v[32:47], v[222:225], v[128:131], v[32:47]
	v_mul_f32_e64 v22, v22, v12
	v_mul_f32_e64 v23, v23, v13
	v_mul_f32_e64 v18, v18, v8
	v_mul_f32_e64 v19, v19, v9
	v_mul_f32_e64 v16, v16, v6
	v_mul_f32_e64 v17, v17, v7
	s_nop 1
	v_mfma_f32_32x32x16_bf16 v[16:31], v[222:225], v[218:221], v[16:31]
	v_mfma_f32_32x32x16_bf16 v[64:79], v[210:213], v[214:217], v[64:79]
	s_waitcnt lgkmcnt(1)
	v_mfma_f32_32x32x16_bf16 v[48:63], v[210:213], v[226:229], v[48:63]
	s_waitcnt lgkmcnt(0)
	v_mfma_f32_32x32x16_bf16 v[32:47], v[2:5], v[214:217], v[32:47]
	v_mfma_f32_32x32x16_bf16 v[16:31], v[2:5], v[226:229], v[16:31]
	ds_read_b128 v[2:5], v206 offset:33856
	ds_read_b128 v[6:9], v207 offset:64
	ds_read_b128 v[10:13], v206 offset:33888
	ds_read_b128 v[210:213], v207 offset:96
	ds_read_b128 v[214:217], v207 offset:4672
	ds_read_b128 v[218:221], v207 offset:4704
	s_waitcnt lgkmcnt(4)
	v_mfma_f32_32x32x16_bf16 v[64:79], v[2:5], v[6:9], v[64:79]
	s_waitcnt lgkmcnt(1)
	v_mfma_f32_32x32x16_bf16 v[48:63], v[2:5], v[214:217], v[48:63]
	ds_read_b128 v[2:5], v206 offset:38464
	ds_read_b128 v[222:225], v206 offset:38496
	s_waitcnt lgkmcnt(1)
	v_mfma_f32_32x32x16_bf16 v[32:47], v[2:5], v[6:9], v[32:47]
	v_mfma_f32_32x32x16_bf16 v[16:31], v[2:5], v[214:217], v[16:31]
	v_mfma_f32_32x32x16_bf16 v[64:79], v[10:13], v[210:213], v[64:79]
	v_mfma_f32_32x32x16_bf16 v[48:63], v[10:13], v[218:221], v[48:63]
	s_waitcnt lgkmcnt(0)
	v_mfma_f32_32x32x16_bf16 v[32:47], v[222:225], v[210:213], v[32:47]
	v_mfma_f32_32x32x16_bf16 v[16:31], v[222:225], v[218:221], v[16:31]
; __device__ __forceinline__ void gla_scan_phase(const Ctx& c, LAS unsigned char* lds) {
;     ...
;             if (wid < 4) {
;                 const int ib = wid & 1, eb = wid >> 1; f32x16 acc2 = {};
; #pragma unroll 4
;                 for (int ks = 0; ks < 16; ks += 2) {
;                     const bf16x8 a = *(const LAS bf16x8*)(lds + SC_QD + (32 * ib + r32) * 528 + (ks * 16 + hi * 8) * 2);
;                     const bf16x8 bb = *(const LAS bf16x8*)(lds + SC_ST + (32 * eb + r32) * 528 + (ks * 16 + hi * 8) * 2);
;                     const bf16x8 a2 = *(const LAS bf16x8*)(lds + SC_QD + (32 * ib + r32) * 528 + ((ks + 1) * 16 + hi * 8) * 2);
;                     const bf16x8 bb2 = *(const LAS bf16x8*)(lds + SC_ST + (32 * eb + r32) * 528 + ((ks + 1) * 16 + hi * 8) * 2);
;                     acc = __builtin_amdgcn_mfma_f32_32x32x16_bf16(a, bb, acc, 0, 0, 0);
;                     acc2 = __builtin_amdgcn_mfma_f32_32x32x16_bf16(a2, bb2, acc2, 0, 0, 0); }
; #pragma unroll
;                 for (int ks = 0; ks < 4; ks += 2) {
;                     const bf16x8 a = *(const LAS bf16x8*)(lds + SC_PM + (32 * ib + r32) * 144 + (ks * 16 + hi * 8) * 2);
;                     const bf16x8 bb = *(const LAS bf16x8*)(lds + SC_VT + (32 * eb + r32) * 144 + (ks * 16 + hi * 8) * 2);
;                     const bf16x8 a2 = *(const LAS bf16x8*)(lds + SC_PM + (32 * ib + r32) * 144 + ((ks + 1) * 16 + hi * 8) * 2);
;                     const bf16x8 bb2 = *(const LAS bf16x8*)(lds + SC_VT + (32 * eb + r32) * 144 + ((ks + 1) * 16 + hi * 8) * 2);
;                     acc = __builtin_amdgcn_mfma_f32_32x32x16_bf16(a, bb, acc, 0, 0, 0);
;                     acc2 = __builtin_amdgcn_mfma_f32_32x32x16_bf16(a2, bb2, acc2, 0, 0, 0); }
; #pragma unroll
;                 for (int r = 0; r < 16; ++r) acc[r] += acc2[r];
;     ...
;             __builtin_amdgcn_s_setprio(0);
;             __syncthreads();
;             if (wid >= 4) { const int jj = wid - 4;
; #pragma unroll
;                 for (int t = 0; t < 4; ++t) { const int db = 2 * jj + (t >> 1), eb = t & 1;
; #pragma unroll
;                     for (int g4 = 0; g4 < 4; ++g4) { u32x2 w; w.x = pk2(sacc[t][4 * g4], sacc[t][4 * g4 + 1]); w.y = pk2(sacc[t][4 * g4 + 2], sacc[t][4 * g4 + 3]);
;                         *(LAS u32x2*)(lds + SC_ST + (32 * eb + r32) * 528 + (32 * db + 8 * g4 + 4 * hi) * 2) = w; } } }
.LBB0_1716:
	v_mov_b32_e32 v3, 0
	s_andn2_b64 vcc, exec, s[60:61]
	v_mov_b32_e32 v2, 0
	v_mov_b32_e32 v5, 0
	v_mov_b32_e32 v4, 0
	v_mov_b32_e32 v7, 0
	v_mov_b32_e32 v6, 0
	v_mov_b32_e32 v9, 0
	v_mov_b32_e32 v8, 0
	v_mov_b32_e32 v11, 0
	v_mov_b32_e32 v10, 0
	v_mov_b32_e32 v13, 0
	v_mov_b32_e32 v12, 0
	v_mov_b32_e32 v15, 0
	v_mov_b32_e32 v14, 0
	v_mov_b32_e32 v195, 0
	v_mov_b32_e32 v194, 0
	s_cbranch_vccnz .Lscan_join_b
	v_add_u32_e32 v72, v197, v196
	v_add_u32_e32 v73, v204, v196
	v_add_u32_e32 v73, 0x15c00, v73
	ds_read_b128 v[16:19], v72
	ds_read_b128 v[20:23], v73
	ds_read_b128 v[24:27], v72 offset:32
	ds_read_b128 v[28:31], v73 offset:32
	ds_read_b128 v[32:35], v72 offset:64
	ds_read_b128 v[36:39], v73 offset:64
	ds_read_b128 v[40:43], v72 offset:96
	ds_read_b128 v[44:47], v73 offset:96
	ds_read_b128 v[48:51], v72 offset:128
	ds_read_b128 v[52:55], v73 offset:128
	ds_read_b128 v[56:59], v72 offset:160
	ds_read_b128 v[60:63], v73 offset:160
	ds_read_b128 v[64:67], v72 offset:192
	ds_read_b128 v[68:71], v73 offset:192
	s_waitcnt lgkmcnt(12)
	v_mfma_f32_32x32x16_bf16 v[80:95], v[16:19], v[20:23], 0
	ds_read_b128 v[16:19], v72 offset:224
	ds_read_b128 v[20:23], v73 offset:224
	s_waitcnt lgkmcnt(12)
	v_mfma_f32_32x32x16_bf16 v[96:111], v[24:27], v[28:31], 0
	ds_read_b128 v[24:27], v72 offset:256
	ds_read_b128 v[28:31], v73 offset:256
	s_waitcnt lgkmcnt(12)
	v_mfma_f32_32x32x16_bf16 v[80:95], v[32:35], v[36:39], v[80:95]
	ds_read_b128 v[32:35], v72 offset:288
	ds_read_b128 v[36:39], v73 offset:288
	s_waitcnt lgkmcnt(12)
	v_mfma_f32_32x32x16_bf16 v[96:111], v[40:43], v[44:47], v[96:111]
	ds_read_b128 v[40:43], v72 offset:320
	ds_read_b128 v[44:47], v73 offset:320
	s_waitcnt lgkmcnt(12)
	v_mfma_f32_32x32x16_bf16 v[80:95], v[48:51], v[52:55], v[80:95]
	ds_read_b128 v[48:51], v72 offset:352
	ds_read_b128 v[52:55], v73 offset:352
	s_waitcnt lgkmcnt(12)
	v_mfma_f32_32x32x16_bf16 v[96:111], v[56:59], v[60:63], v[96:111]
	ds_read_b128 v[56:59], v72 offset:384
	ds_read_b128 v[60:63], v73 offset:384
	s_waitcnt lgkmcnt(12)
	v_mfma_f32_32x32x16_bf16 v[80:95], v[64:67], v[68:71], v[80:95]
	ds_read_b128 v[64:67], v72 offset:416
	ds_read_b128 v[68:71], v73 offset:416
	s_waitcnt lgkmcnt(12)
	v_mfma_f32_32x32x16_bf16 v[96:111], v[16:19], v[20:23], v[96:111]
	ds_read_b128 v[16:19], v72 offset:448
	ds_read_b128 v[20:23], v73 offset:448
	s_waitcnt lgkmcnt(12)
	v_mfma_f32_32x32x16_bf16 v[80:95], v[24:27], v[28:31], v[80:95]
	ds_read_b128 v[24:27], v72 offset:480
	ds_read_b128 v[28:31], v73 offset:480
	s_waitcnt lgkmcnt(12)
	v_mfma_f32_32x32x16_bf16 v[96:111], v[32:35], v[36:39], v[96:111]
	ds_read_b128 v[32:35], v208
	ds_read_b128 v[36:39], v209
	s_waitcnt lgkmcnt(12)
	v_mfma_f32_32x32x16_bf16 v[80:95], v[40:43], v[44:47], v[80:95]
	ds_read_b128 v[40:43], v208 offset:32
	ds_read_b128 v[44:47], v209 offset:32
	s_waitcnt lgkmcnt(12)
	v_mfma_f32_32x32x16_bf16 v[96:111], v[48:51], v[52:55], v[96:111]
	ds_read_b128 v[48:51], v208 offset:64
	ds_read_b128 v[52:55], v209 offset:64
	s_waitcnt lgkmcnt(12)
	v_mfma_f32_32x32x16_bf16 v[80:95], v[56:59], v[60:63], v[80:95]
	ds_read_b128 v[56:59], v208 offset:96
	ds_read_b128 v[60:63], v209 offset:96
	s_waitcnt lgkmcnt(12)
	v_mfma_f32_32x32x16_bf16 v[96:111], v[64:67], v[68:71], v[96:111]
	s_waitcnt lgkmcnt(10)
	v_mfma_f32_32x32x16_bf16 v[80:95], v[16:19], v[20:23], v[80:95]
	s_waitcnt lgkmcnt(8)
	v_mfma_f32_32x32x16_bf16 v[96:111], v[24:27], v[28:31], v[96:111]
	s_waitcnt lgkmcnt(6)
	v_mfma_f32_32x32x16_bf16 v[80:95], v[32:35], v[36:39], v[80:95]
	s_waitcnt lgkmcnt(4)
	v_mfma_f32_32x32x16_bf16 v[96:111], v[40:43], v[44:47], v[96:111]
	s_waitcnt lgkmcnt(2)
	v_mfma_f32_32x32x16_bf16 v[80:95], v[48:51], v[52:55], v[80:95]
	s_waitcnt lgkmcnt(0)
	v_mfma_f32_32x32x16_bf16 v[96:111], v[56:59], v[60:63], v[96:111]
	s_nop 11
	v_pk_add_f32 v[2:3], v[94:95], v[110:111]
	v_pk_add_f32 v[4:5], v[92:93], v[108:109]
	v_pk_add_f32 v[6:7], v[90:91], v[106:107]
	v_pk_add_f32 v[8:9], v[88:89], v[104:105]
	v_pk_add_f32 v[10:11], v[86:87], v[102:103]
	v_pk_add_f32 v[12:13], v[84:85], v[100:101]
	v_pk_add_f32 v[14:15], v[82:83], v[98:99]
	v_pk_add_f32 v[194:195], v[80:81], v[96:97]
	s_branch .Lscan_join_b
.Lscan_join_b:
	s_setprio 0
	s_andn2_b64 vcc, exec, s[20:21]
	s_barrier
	s_cbranch_vccnz .LBB0_1722
	v_cvt_pk_bf16_f32 v80, v64, v65
	v_cvt_pk_bf16_f32 v81, v66, v67
	v_add_u32_e32 v1, s84, v201
	v_cvt_pk_bf16_f32 v82, v68, v69
	v_cvt_pk_bf16_f32 v83, v70, v71
	ds_write2_b64 v1, v[80:81], v[82:83] offset1:2
	v_cvt_pk_bf16_f32 v80, v72, v73
	v_cvt_pk_bf16_f32 v81, v74, v75
	v_cvt_pk_bf16_f32 v82, v76, v77
	v_cvt_pk_bf16_f32 v83, v78, v79
	ds_write2_b64 v1, v[80:81], v[82:83] offset0:4 offset1:6
	v_add_u32_e32 v1, s83, v201
	v_cvt_pk_bf16_f32 v80, v48, v49
	v_cvt_pk_bf16_f32 v81, v50, v51
	v_cvt_pk_bf16_f32 v82, v52, v53
	v_cvt_pk_bf16_f32 v83, v54, v55
	v_add_u32_e32 v1, 0x4000, v1
	ds_write2_b64 v1, v[80:81], v[82:83] offset1:2
	v_cvt_pk_bf16_f32 v80, v56, v57
	v_cvt_pk_bf16_f32 v81, v58, v59
	v_cvt_pk_bf16_f32 v82, v60, v61
	v_cvt_pk_bf16_f32 v83, v62, v63
	ds_write2_b64 v1, v[80:81], v[82:83] offset0:4 offset1:6
	v_cvt_pk_bf16_f32 v80, v32, v33
	v_cvt_pk_bf16_f32 v81, v34, v35
	v_add_u32_e32 v84, s85, v201
	v_cvt_pk_bf16_f32 v82, v36, v37
	v_cvt_pk_bf16_f32 v83, v38, v39
	ds_write2_b64 v84, v[80:81], v[82:83] offset1:2
	v_cvt_pk_bf16_f32 v80, v40, v41
	v_cvt_pk_bf16_f32 v81, v42, v43
	v_cvt_pk_bf16_f32 v82, v44, v45
	v_cvt_pk_bf16_f32 v83, v46, v47
	ds_write2_b64 v84, v[80:81], v[82:83] offset0:4 offset1:6
	v_cvt_pk_bf16_f32 v80, v16, v17
	v_cvt_pk_bf16_f32 v81, v18, v19
	v_cvt_pk_bf16_f32 v82, v20, v21
	v_cvt_pk_bf16_f32 v83, v22, v23
	ds_write2_b64 v1, v[80:81], v[82:83] offset0:8 offset1:10
	v_cvt_pk_bf16_f32 v80, v24, v25
	v_cvt_pk_bf16_f32 v81, v26, v27
	v_cvt_pk_bf16_f32 v82, v28, v29
	v_cvt_pk_bf16_f32 v83, v30, v31
	ds_write2_b64 v1, v[80:81], v[82:83] offset0:12 offset1:14
